# v47
# speedup vs baseline: 1.0226x; 1.0146x over previous
; DI float dpp_xor1(float x) { return __int_as_float(__builtin_amdgcn_mov_dpp(__float_as_int(x), 0xB1, 0xF, 0xF, true)); }
; DI float dpp_xor2(float x) { return __int_as_float(__builtin_amdgcn_mov_dpp(__float_as_int(x), 0x4E, 0xF, 0xF, true)); }
; DI float dpp_hm(float x) { return __int_as_float(__builtin_amdgcn_mov_dpp(__float_as_int(x), 0x141, 0xF, 0xF, true)); }
; DI float dpp_rm(float x) { return __int_as_float(__builtin_amdgcn_mov_dpp(__float_as_int(x), 0x140, 0xF, 0xF, true)); }
; DI void rwkv_scan_task1(const Params& p, const Grp& G, int unit, char* lds) {
;     ...
;       const float* b0 = cur + part * 4;
;       float4 kkA = *(const float4*)(b0 + 3 * 64), wA = *(const float4*)(b0 + 1 * 64), kaA = *(const float4*)(b0 + 4 * 64);
;       float4 kdA = *(const float4*)(b0 + 2 * 64), rrA = *(const float4*)(b0);
;       float vvA = cur[5 * 64 + vrow];
;       float ykeep = 0.f, ypA = 0.f;
; #pragma unroll
;       for (int st = 0; st < 16; ++st) {
;         float4 kkB = kkA, wB = wA, kaB = kaA, kdB = kdA, rrB = rrA;
;         float vvB = vvA;
;         if (st < 15) {
;           const float* b = cur + (st + 1) * 384 + part * 4;
;           kkB = *(const float4*)(b + 3 * 64); wB = *(const float4*)(b + 1 * 64); kaB = *(const float4*)(b + 4 * 64);
;           kdB = *(const float4*)(b + 2 * 64); rrB = *(const float4*)(b);
;           vvB = cur[(st + 1) * 384 + 5 * 64 + vrow];
;         }
;         float ra = (S0 * kkA.x + S1 * kkA.y) + (S2 * kkA.z + S3 * kkA.w), rc = ypA;
;         ra += dpp_xor1(ra); rc += dpp_xor1(rc);
;         ra += dpp_xor2(ra); rc += dpp_xor2(rc);
;         ra += dpp_hm(ra); rc += dpp_hm(rc);
;         ra += dpp_rm(ra); rc += dpp_rm(rc);
;         if (st > 0) ykeep = (part == st - 1) ? rc : ykeep;
;         const float sa = ra;
;         S0 = S0 * wA.x + (sa * kaA.x + vvA * kdA.x);
;         S1 = S1 * wA.y + (sa * kaA.y + vvA * kdA.y);
;         S2 = S2 * wA.z + (sa * kaA.z + vvA * kdA.z);
;         S3 = S3 * wA.w + (sa * kaA.w + vvA * kdA.w);
;         ypA = (S0 * rrA.x + S1 * rrA.y) + (S2 * rrA.z + S3 * rrA.w);
;         kkA = kkB; wA = wB; kaA = kaB; kdA = kdB; rrA = rrB; vvA = vvB;
.LBB0_877:
	s_bitcmp1_b32 s42, 0
	s_cselect_b32 s42, 0x6000, 0
	v_lshl_or_b32 v72, v47, 2, s42
	v_lshl_add_u32 v73, v46, 2, s42
	ds_read_b128 v[88:91], v72 offset:768
	ds_read_b128 v[84:87], v72 offset:512
	ds_read_b32 v96, v73 offset:1280
	ds_read_b128 v[80:83], v72 offset:256
	ds_read_b128 v[92:95], v72 offset:1024
	ds_read_b128 v[76:79], v72 offset:0
	s_waitcnt lgkmcnt(0)
	ds_read_b128 v[112:115], v72 offset:2304
	ds_read_b128 v[108:111], v72 offset:2048
	ds_read_b32 v120, v73 offset:2816
	ds_read_b128 v[104:107], v72 offset:1792
	ds_read_b128 v[116:119], v72 offset:2560
	ds_read_b128 v[100:103], v72 offset:1536
	v_pk_mul_f32 v[130:131], v[56:57], v[88:89]
	v_pk_mul_f32 v[126:127], v[84:85], v[96:97] op_sel_hi:[1,0]
	v_pk_fma_f32 v[130:131], v[60:61], v[90:91], v[130:131]
	v_pk_mul_f32 v[128:129], v[86:87], v[96:97] op_sel_hi:[1,0]
	v_add_f32_e32 v124, v130, v131
	v_pk_fma_f32 v[126:127], v[56:57], v[80:81], v[126:127]
	v_pk_fma_f32 v[128:129], v[60:61], v[82:83], v[128:129]
	v_add_f32_dpp v124, v124, v124 quad_perm:[1,0,3,2] row_mask:0xf bank_mask:0xf bound_ctrl:1
	s_nop 0
	s_nop 0
	v_add_f32_dpp v124, v124, v124 quad_perm:[2,3,0,1] row_mask:0xf bank_mask:0xf bound_ctrl:1
	s_nop 0
	s_nop 0
	v_add_f32_dpp v124, v124, v124 row_half_mirror row_mask:0xf bank_mask:0xf bound_ctrl:1
	s_nop 0
	s_nop 0
	v_add_f32_dpp v124, v124, v124 row_mirror row_mask:0xf bank_mask:0xf bound_ctrl:1
	v_pk_fma_f32 v[56:57], v[92:93], v[124:125], v[126:127] op_sel_hi:[1,0,1]
	v_pk_fma_f32 v[60:61], v[94:95], v[124:125], v[128:129] op_sel_hi:[1,0,1]
	v_pk_mul_f32 v[130:131], v[56:57], v[76:77]
	s_nop 0
	v_pk_fma_f32 v[130:131], v[60:61], v[78:79], v[130:131]
	s_nop 0
	v_add_f32_e32 v140, v130, v131
	s_waitcnt lgkmcnt(0)
	ds_read_b128 v[88:91], v72 offset:3840
	ds_read_b128 v[84:87], v72 offset:3584
	ds_read_b32 v96, v73 offset:4352
	ds_read_b128 v[80:83], v72 offset:3328
	ds_read_b128 v[92:95], v72 offset:4096
	ds_read_b128 v[76:79], v72 offset:3072
	v_pk_mul_f32 v[130:131], v[56:57], v[112:113]
	v_pk_mul_f32 v[126:127], v[108:109], v[120:121] op_sel_hi:[1,0]
	v_pk_fma_f32 v[130:131], v[60:61], v[114:115], v[130:131]
	v_pk_mul_f32 v[128:129], v[110:111], v[120:121] op_sel_hi:[1,0]
	v_add_f32_e32 v124, v130, v131
	v_pk_fma_f32 v[126:127], v[56:57], v[104:105], v[126:127]
	v_pk_fma_f32 v[128:129], v[60:61], v[106:107], v[128:129]
	v_add_f32_dpp v124, v124, v124 quad_perm:[1,0,3,2] row_mask:0xf bank_mask:0xf bound_ctrl:1
	s_nop 0
	s_nop 0
	v_add_f32_dpp v124, v124, v124 quad_perm:[2,3,0,1] row_mask:0xf bank_mask:0xf bound_ctrl:1
	s_nop 0
	s_nop 0
	v_add_f32_dpp v124, v124, v124 row_half_mirror row_mask:0xf bank_mask:0xf bound_ctrl:1
	s_nop 0
	s_nop 0
	v_add_f32_dpp v124, v124, v124 row_mirror row_mask:0xf bank_mask:0xf bound_ctrl:1
	v_pk_fma_f32 v[56:57], v[116:117], v[124:125], v[126:127] op_sel_hi:[1,0,1]
	v_pk_fma_f32 v[60:61], v[118:119], v[124:125], v[128:129] op_sel_hi:[1,0,1]
	v_pk_mul_f32 v[130:131], v[56:57], v[100:101]
	s_nop 0
	v_pk_fma_f32 v[130:131], v[60:61], v[102:103], v[130:131]
	s_nop 0
	v_add_f32_e32 v141, v130, v131
	s_waitcnt lgkmcnt(0)
	ds_read_b128 v[112:115], v72 offset:5376
	ds_read_b128 v[108:111], v72 offset:5120
	ds_read_b32 v120, v73 offset:5888
	ds_read_b128 v[104:107], v72 offset:4864
	ds_read_b128 v[116:119], v72 offset:5632
	ds_read_b128 v[100:103], v72 offset:4608
	v_pk_mul_f32 v[130:131], v[56:57], v[88:89]
	v_pk_mul_f32 v[126:127], v[84:85], v[96:97] op_sel_hi:[1,0]
	v_pk_fma_f32 v[130:131], v[60:61], v[90:91], v[130:131]
	v_pk_mul_f32 v[128:129], v[86:87], v[96:97] op_sel_hi:[1,0]
	v_add_f32_e32 v124, v130, v131
	v_pk_fma_f32 v[126:127], v[56:57], v[80:81], v[126:127]
	v_pk_fma_f32 v[128:129], v[60:61], v[82:83], v[128:129]
	v_add_f32_dpp v124, v124, v124 quad_perm:[1,0,3,2] row_mask:0xf bank_mask:0xf bound_ctrl:1
	s_nop 0
	s_nop 0
	v_add_f32_dpp v124, v124, v124 quad_perm:[2,3,0,1] row_mask:0xf bank_mask:0xf bound_ctrl:1
	s_nop 0
	s_nop 0
	v_add_f32_dpp v124, v124, v124 row_half_mirror row_mask:0xf bank_mask:0xf bound_ctrl:1
	s_nop 0
	s_nop 0
	v_add_f32_dpp v124, v124, v124 row_mirror row_mask:0xf bank_mask:0xf bound_ctrl:1
	v_pk_fma_f32 v[56:57], v[92:93], v[124:125], v[126:127] op_sel_hi:[1,0,1]
	v_pk_fma_f32 v[60:61], v[94:95], v[124:125], v[128:129] op_sel_hi:[1,0,1]
	v_pk_mul_f32 v[130:131], v[56:57], v[76:77]
	s_nop 0
	v_pk_fma_f32 v[130:131], v[60:61], v[78:79], v[130:131]
	s_nop 0
	v_add_f32_e32 v142, v130, v131
	s_waitcnt lgkmcnt(0)
	ds_read_b128 v[88:91], v72 offset:6912
	ds_read_b128 v[84:87], v72 offset:6656
	ds_read_b32 v96, v73 offset:7424
	ds_read_b128 v[80:83], v72 offset:6400
	ds_read_b128 v[92:95], v72 offset:7168
	ds_read_b128 v[76:79], v72 offset:6144
	v_pk_mul_f32 v[130:131], v[56:57], v[112:113]
	v_pk_mul_f32 v[126:127], v[108:109], v[120:121] op_sel_hi:[1,0]
	v_pk_fma_f32 v[130:131], v[60:61], v[114:115], v[130:131]
	v_pk_mul_f32 v[128:129], v[110:111], v[120:121] op_sel_hi:[1,0]
	v_add_f32_e32 v124, v130, v131
	v_pk_fma_f32 v[126:127], v[56:57], v[104:105], v[126:127]
	v_pk_fma_f32 v[128:129], v[60:61], v[106:107], v[128:129]
	v_add_f32_dpp v124, v124, v124 quad_perm:[1,0,3,2] row_mask:0xf bank_mask:0xf bound_ctrl:1
	s_nop 0
	s_nop 0
	v_add_f32_dpp v124, v124, v124 quad_perm:[2,3,0,1] row_mask:0xf bank_mask:0xf bound_ctrl:1
	s_nop 0
	s_nop 0
	v_add_f32_dpp v124, v124, v124 row_half_mirror row_mask:0xf bank_mask:0xf bound_ctrl:1
	s_nop 0
	s_nop 0
	v_add_f32_dpp v124, v124, v124 row_mirror row_mask:0xf bank_mask:0xf bound_ctrl:1
	v_pk_fma_f32 v[56:57], v[116:117], v[124:125], v[126:127] op_sel_hi:[1,0,1]
	v_pk_fma_f32 v[60:61], v[118:119], v[124:125], v[128:129] op_sel_hi:[1,0,1]
	v_pk_mul_f32 v[130:131], v[56:57], v[100:101]
	s_nop 0
	v_pk_fma_f32 v[130:131], v[60:61], v[102:103], v[130:131]
	s_nop 0
	v_add_f32_e32 v143, v130, v131
	s_waitcnt lgkmcnt(0)
; DI float dpp_xor1(float x) { return __int_as_float(__builtin_amdgcn_mov_dpp(__float_as_int(x), 0xB1, 0xF, 0xF, true)); }
; DI float dpp_xor2(float x) { return __int_as_float(__builtin_amdgcn_mov_dpp(__float_as_int(x), 0x4E, 0xF, 0xF, true)); }
; DI float dpp_hm(float x) { return __int_as_float(__builtin_amdgcn_mov_dpp(__float_as_int(x), 0x141, 0xF, 0xF, true)); }
; DI float dpp_rm(float x) { return __int_as_float(__builtin_amdgcn_mov_dpp(__float_as_int(x), 0x140, 0xF, 0xF, true)); }
; DI void rwkv_scan_task1(const Params& p, const Grp& G, int unit, char* lds) {
;     ...
;       for (int st = 0; st < 16; ++st) {
;         float4 kkB = kkA, wB = wA, kaB = kaA, kdB = kdA, rrB = rrA;
;         float vvB = vvA;
;         if (st < 15) {
;           const float* b = cur + (st + 1) * 384 + part * 4;
;           kkB = *(const float4*)(b + 3 * 64); wB = *(const float4*)(b + 1 * 64); kaB = *(const float4*)(b + 4 * 64);
;           kdB = *(const float4*)(b + 2 * 64); rrB = *(const float4*)(b);
;           vvB = cur[(st + 1) * 384 + 5 * 64 + vrow];
;         }
;         float ra = (S0 * kkA.x + S1 * kkA.y) + (S2 * kkA.z + S3 * kkA.w), rc = ypA;
;         ra += dpp_xor1(ra); rc += dpp_xor1(rc);
;         ra += dpp_xor2(ra); rc += dpp_xor2(rc);
;         ra += dpp_hm(ra); rc += dpp_hm(rc);
;         ra += dpp_rm(ra); rc += dpp_rm(rc);
;         if (st > 0) ykeep = (part == st - 1) ? rc : ykeep;
;         const float sa = ra;
;         S0 = S0 * wA.x + (sa * kaA.x + vvA * kdA.x);
;         S1 = S1 * wA.y + (sa * kaA.y + vvA * kdA.y);
;         S2 = S2 * wA.z + (sa * kaA.z + vvA * kdA.z);
;         S3 = S3 * wA.w + (sa * kaA.w + vvA * kdA.w);
;         ypA = (S0 * rrA.x + S1 * rrA.y) + (S2 * rrA.z + S3 * rrA.w);
;         kkA = kkB; wA = wB; kaA = kaB; kdA = kdB; rrA = rrB; vvA = vvB;
	ds_read_b128 v[112:115], v72 offset:8448
	ds_read_b128 v[108:111], v72 offset:8192
	ds_read_b32 v120, v73 offset:8960
	ds_read_b128 v[104:107], v72 offset:7936
	ds_read_b128 v[116:119], v72 offset:8704
	ds_read_b128 v[100:103], v72 offset:7680
	v_pk_mul_f32 v[130:131], v[56:57], v[88:89]
	v_pk_mul_f32 v[126:127], v[84:85], v[96:97] op_sel_hi:[1,0]
	v_pk_fma_f32 v[130:131], v[60:61], v[90:91], v[130:131]
	v_pk_mul_f32 v[128:129], v[86:87], v[96:97] op_sel_hi:[1,0]
	v_add_f32_e32 v124, v130, v131
	v_pk_fma_f32 v[126:127], v[56:57], v[80:81], v[126:127]
	v_pk_fma_f32 v[128:129], v[60:61], v[82:83], v[128:129]
	v_add_f32_dpp v124, v124, v124 quad_perm:[1,0,3,2] row_mask:0xf bank_mask:0xf bound_ctrl:1
	s_nop 0
	s_nop 0
	v_add_f32_dpp v124, v124, v124 quad_perm:[2,3,0,1] row_mask:0xf bank_mask:0xf bound_ctrl:1
	s_nop 0
	s_nop 0
	v_add_f32_dpp v124, v124, v124 row_half_mirror row_mask:0xf bank_mask:0xf bound_ctrl:1
	s_nop 0
	s_nop 0
	v_add_f32_dpp v124, v124, v124 row_mirror row_mask:0xf bank_mask:0xf bound_ctrl:1
	v_pk_fma_f32 v[56:57], v[92:93], v[124:125], v[126:127] op_sel_hi:[1,0,1]
	v_pk_fma_f32 v[60:61], v[94:95], v[124:125], v[128:129] op_sel_hi:[1,0,1]
	v_pk_mul_f32 v[130:131], v[56:57], v[76:77]
	s_nop 0
	v_pk_fma_f32 v[130:131], v[60:61], v[78:79], v[130:131]
	s_nop 0
	v_add_f32_e32 v144, v130, v131
	s_waitcnt lgkmcnt(0)
	ds_read_b128 v[88:91], v72 offset:9984
	ds_read_b128 v[84:87], v72 offset:9728
	ds_read_b32 v96, v73 offset:10496
	ds_read_b128 v[80:83], v72 offset:9472
	ds_read_b128 v[92:95], v72 offset:10240
	ds_read_b128 v[76:79], v72 offset:9216
	v_pk_mul_f32 v[130:131], v[56:57], v[112:113]
	v_pk_mul_f32 v[126:127], v[108:109], v[120:121] op_sel_hi:[1,0]
	v_pk_fma_f32 v[130:131], v[60:61], v[114:115], v[130:131]
	v_pk_mul_f32 v[128:129], v[110:111], v[120:121] op_sel_hi:[1,0]
	v_add_f32_e32 v124, v130, v131
	v_pk_fma_f32 v[126:127], v[56:57], v[104:105], v[126:127]
	v_pk_fma_f32 v[128:129], v[60:61], v[106:107], v[128:129]
	v_add_f32_dpp v124, v124, v124 quad_perm:[1,0,3,2] row_mask:0xf bank_mask:0xf bound_ctrl:1
	s_nop 0
	s_nop 0
	v_add_f32_dpp v124, v124, v124 quad_perm:[2,3,0,1] row_mask:0xf bank_mask:0xf bound_ctrl:1
	s_nop 0
	s_nop 0
	v_add_f32_dpp v124, v124, v124 row_half_mirror row_mask:0xf bank_mask:0xf bound_ctrl:1
	s_nop 0
	s_nop 0
	v_add_f32_dpp v124, v124, v124 row_mirror row_mask:0xf bank_mask:0xf bound_ctrl:1
	v_pk_fma_f32 v[56:57], v[116:117], v[124:125], v[126:127] op_sel_hi:[1,0,1]
	v_pk_fma_f32 v[60:61], v[118:119], v[124:125], v[128:129] op_sel_hi:[1,0,1]
	v_pk_mul_f32 v[130:131], v[56:57], v[100:101]
	s_nop 0
	v_pk_fma_f32 v[130:131], v[60:61], v[102:103], v[130:131]
	s_nop 0
	v_add_f32_e32 v145, v130, v131
	s_waitcnt lgkmcnt(0)
	ds_read_b128 v[112:115], v72 offset:11520
	ds_read_b128 v[108:111], v72 offset:11264
	ds_read_b32 v120, v73 offset:12032
	ds_read_b128 v[104:107], v72 offset:11008
	ds_read_b128 v[116:119], v72 offset:11776
	ds_read_b128 v[100:103], v72 offset:10752
	v_pk_mul_f32 v[130:131], v[56:57], v[88:89]
	v_pk_mul_f32 v[126:127], v[84:85], v[96:97] op_sel_hi:[1,0]
	v_pk_fma_f32 v[130:131], v[60:61], v[90:91], v[130:131]
	v_pk_mul_f32 v[128:129], v[86:87], v[96:97] op_sel_hi:[1,0]
	v_add_f32_e32 v124, v130, v131
	v_pk_fma_f32 v[126:127], v[56:57], v[80:81], v[126:127]
	v_pk_fma_f32 v[128:129], v[60:61], v[82:83], v[128:129]
	v_add_f32_dpp v124, v124, v124 quad_perm:[1,0,3,2] row_mask:0xf bank_mask:0xf bound_ctrl:1
	s_nop 0
	s_nop 0
	v_add_f32_dpp v124, v124, v124 quad_perm:[2,3,0,1] row_mask:0xf bank_mask:0xf bound_ctrl:1
	s_nop 0
	s_nop 0
	v_add_f32_dpp v124, v124, v124 row_half_mirror row_mask:0xf bank_mask:0xf bound_ctrl:1
	s_nop 0
	s_nop 0
	v_add_f32_dpp v124, v124, v124 row_mirror row_mask:0xf bank_mask:0xf bound_ctrl:1
	v_pk_fma_f32 v[56:57], v[92:93], v[124:125], v[126:127] op_sel_hi:[1,0,1]
	v_pk_fma_f32 v[60:61], v[94:95], v[124:125], v[128:129] op_sel_hi:[1,0,1]
	v_pk_mul_f32 v[130:131], v[56:57], v[76:77]
	s_nop 0
	v_pk_fma_f32 v[130:131], v[60:61], v[78:79], v[130:131]
	s_nop 0
	v_add_f32_e32 v146, v130, v131
	s_waitcnt lgkmcnt(0)
	ds_read_b128 v[88:91], v72 offset:13056
	ds_read_b128 v[84:87], v72 offset:12800
	ds_read_b32 v96, v73 offset:13568
	ds_read_b128 v[80:83], v72 offset:12544
	ds_read_b128 v[92:95], v72 offset:13312
	ds_read_b128 v[76:79], v72 offset:12288
	v_pk_mul_f32 v[130:131], v[56:57], v[112:113]
	v_pk_mul_f32 v[126:127], v[108:109], v[120:121] op_sel_hi:[1,0]
	v_pk_fma_f32 v[130:131], v[60:61], v[114:115], v[130:131]
	v_pk_mul_f32 v[128:129], v[110:111], v[120:121] op_sel_hi:[1,0]
	v_add_f32_e32 v124, v130, v131
	v_pk_fma_f32 v[126:127], v[56:57], v[104:105], v[126:127]
	v_pk_fma_f32 v[128:129], v[60:61], v[106:107], v[128:129]
	v_add_f32_dpp v124, v124, v124 quad_perm:[1,0,3,2] row_mask:0xf bank_mask:0xf bound_ctrl:1
	s_nop 0
	s_nop 0
	v_add_f32_dpp v124, v124, v124 quad_perm:[2,3,0,1] row_mask:0xf bank_mask:0xf bound_ctrl:1
	s_nop 0
	s_nop 0
	v_add_f32_dpp v124, v124, v124 row_half_mirror row_mask:0xf bank_mask:0xf bound_ctrl:1
	s_nop 0
	s_nop 0
	v_add_f32_dpp v124, v124, v124 row_mirror row_mask:0xf bank_mask:0xf bound_ctrl:1
	v_pk_fma_f32 v[56:57], v[116:117], v[124:125], v[126:127] op_sel_hi:[1,0,1]
	v_pk_fma_f32 v[60:61], v[118:119], v[124:125], v[128:129] op_sel_hi:[1,0,1]
	v_pk_mul_f32 v[130:131], v[56:57], v[100:101]
	s_nop 0
	v_pk_fma_f32 v[130:131], v[60:61], v[102:103], v[130:131]
	s_nop 0
	v_add_f32_e32 v147, v130, v131
	s_waitcnt lgkmcnt(0)
; DI float dpp_xor1(float x) { return __int_as_float(__builtin_amdgcn_mov_dpp(__float_as_int(x), 0xB1, 0xF, 0xF, true)); }
; DI float dpp_xor2(float x) { return __int_as_float(__builtin_amdgcn_mov_dpp(__float_as_int(x), 0x4E, 0xF, 0xF, true)); }
; DI float dpp_hm(float x) { return __int_as_float(__builtin_amdgcn_mov_dpp(__float_as_int(x), 0x141, 0xF, 0xF, true)); }
; DI float dpp_rm(float x) { return __int_as_float(__builtin_amdgcn_mov_dpp(__float_as_int(x), 0x140, 0xF, 0xF, true)); }
; DI void rwkv_scan_task1(const Params& p, const Grp& G, int unit, char* lds) {
;     ...
;       for (int st = 0; st < 16; ++st) {
;         float4 kkB = kkA, wB = wA, kaB = kaA, kdB = kdA, rrB = rrA;
;         float vvB = vvA;
;         if (st < 15) {
;           const float* b = cur + (st + 1) * 384 + part * 4;
;           kkB = *(const float4*)(b + 3 * 64); wB = *(const float4*)(b + 1 * 64); kaB = *(const float4*)(b + 4 * 64);
;           kdB = *(const float4*)(b + 2 * 64); rrB = *(const float4*)(b);
;           vvB = cur[(st + 1) * 384 + 5 * 64 + vrow];
;         }
;         float ra = (S0 * kkA.x + S1 * kkA.y) + (S2 * kkA.z + S3 * kkA.w), rc = ypA;
;         ra += dpp_xor1(ra); rc += dpp_xor1(rc);
;         ra += dpp_xor2(ra); rc += dpp_xor2(rc);
;         ra += dpp_hm(ra); rc += dpp_hm(rc);
;         ra += dpp_rm(ra); rc += dpp_rm(rc);
;         if (st > 0) ykeep = (part == st - 1) ? rc : ykeep;
;         const float sa = ra;
;         S0 = S0 * wA.x + (sa * kaA.x + vvA * kdA.x);
;         S1 = S1 * wA.y + (sa * kaA.y + vvA * kdA.y);
;         S2 = S2 * wA.z + (sa * kaA.z + vvA * kdA.z);
;         S3 = S3 * wA.w + (sa * kaA.w + vvA * kdA.w);
;         ypA = (S0 * rrA.x + S1 * rrA.y) + (S2 * rrA.z + S3 * rrA.w);
;         kkA = kkB; wA = wB; kaA = kaB; kdA = kdB; rrA = rrB; vvA = vvB;
	ds_read_b128 v[112:115], v72 offset:14592
	ds_read_b128 v[108:111], v72 offset:14336
	ds_read_b32 v120, v73 offset:15104
	ds_read_b128 v[104:107], v72 offset:14080
	ds_read_b128 v[116:119], v72 offset:14848
	ds_read_b128 v[100:103], v72 offset:13824
	v_pk_mul_f32 v[130:131], v[56:57], v[88:89]
	v_pk_mul_f32 v[126:127], v[84:85], v[96:97] op_sel_hi:[1,0]
	v_pk_fma_f32 v[130:131], v[60:61], v[90:91], v[130:131]
	v_pk_mul_f32 v[128:129], v[86:87], v[96:97] op_sel_hi:[1,0]
	v_add_f32_e32 v124, v130, v131
	v_pk_fma_f32 v[126:127], v[56:57], v[80:81], v[126:127]
	v_pk_fma_f32 v[128:129], v[60:61], v[82:83], v[128:129]
	v_add_f32_dpp v124, v124, v124 quad_perm:[1,0,3,2] row_mask:0xf bank_mask:0xf bound_ctrl:1
	s_nop 0
	s_nop 0
	v_add_f32_dpp v124, v124, v124 quad_perm:[2,3,0,1] row_mask:0xf bank_mask:0xf bound_ctrl:1
	s_nop 0
	s_nop 0
	v_add_f32_dpp v124, v124, v124 row_half_mirror row_mask:0xf bank_mask:0xf bound_ctrl:1
	s_nop 0
	s_nop 0
	v_add_f32_dpp v124, v124, v124 row_mirror row_mask:0xf bank_mask:0xf bound_ctrl:1
	v_pk_fma_f32 v[56:57], v[92:93], v[124:125], v[126:127] op_sel_hi:[1,0,1]
	v_pk_fma_f32 v[60:61], v[94:95], v[124:125], v[128:129] op_sel_hi:[1,0,1]
	v_pk_mul_f32 v[130:131], v[56:57], v[76:77]
	s_nop 0
	v_pk_fma_f32 v[130:131], v[60:61], v[78:79], v[130:131]
	s_nop 0
	v_add_f32_e32 v148, v130, v131
	s_waitcnt lgkmcnt(0)
	ds_read_b128 v[88:91], v72 offset:16128
	ds_read_b128 v[84:87], v72 offset:15872
	ds_read_b32 v96, v73 offset:16640
	ds_read_b128 v[80:83], v72 offset:15616
	ds_read_b128 v[92:95], v72 offset:16384
	ds_read_b128 v[76:79], v72 offset:15360
	v_pk_mul_f32 v[130:131], v[56:57], v[112:113]
	v_pk_mul_f32 v[126:127], v[108:109], v[120:121] op_sel_hi:[1,0]
	v_pk_fma_f32 v[130:131], v[60:61], v[114:115], v[130:131]
	v_pk_mul_f32 v[128:129], v[110:111], v[120:121] op_sel_hi:[1,0]
	v_add_f32_e32 v124, v130, v131
	v_pk_fma_f32 v[126:127], v[56:57], v[104:105], v[126:127]
	v_pk_fma_f32 v[128:129], v[60:61], v[106:107], v[128:129]
	v_add_f32_dpp v124, v124, v124 quad_perm:[1,0,3,2] row_mask:0xf bank_mask:0xf bound_ctrl:1
	s_nop 0
	s_nop 0
	v_add_f32_dpp v124, v124, v124 quad_perm:[2,3,0,1] row_mask:0xf bank_mask:0xf bound_ctrl:1
	s_nop 0
	s_nop 0
	v_add_f32_dpp v124, v124, v124 row_half_mirror row_mask:0xf bank_mask:0xf bound_ctrl:1
	s_nop 0
	s_nop 0
	v_add_f32_dpp v124, v124, v124 row_mirror row_mask:0xf bank_mask:0xf bound_ctrl:1
	v_pk_fma_f32 v[56:57], v[116:117], v[124:125], v[126:127] op_sel_hi:[1,0,1]
	v_pk_fma_f32 v[60:61], v[118:119], v[124:125], v[128:129] op_sel_hi:[1,0,1]
	v_pk_mul_f32 v[130:131], v[56:57], v[100:101]
	s_nop 0
	v_pk_fma_f32 v[130:131], v[60:61], v[102:103], v[130:131]
	s_nop 0
	v_add_f32_e32 v149, v130, v131
	s_waitcnt lgkmcnt(0)
	ds_read_b128 v[112:115], v72 offset:17664
	ds_read_b128 v[108:111], v72 offset:17408
	ds_read_b32 v120, v73 offset:18176
	ds_read_b128 v[104:107], v72 offset:17152
	ds_read_b128 v[116:119], v72 offset:17920
	ds_read_b128 v[100:103], v72 offset:16896
	v_pk_mul_f32 v[130:131], v[56:57], v[88:89]
	v_pk_mul_f32 v[126:127], v[84:85], v[96:97] op_sel_hi:[1,0]
	v_pk_fma_f32 v[130:131], v[60:61], v[90:91], v[130:131]
	v_pk_mul_f32 v[128:129], v[86:87], v[96:97] op_sel_hi:[1,0]
	v_add_f32_e32 v124, v130, v131
	v_pk_fma_f32 v[126:127], v[56:57], v[80:81], v[126:127]
	v_pk_fma_f32 v[128:129], v[60:61], v[82:83], v[128:129]
	v_add_f32_dpp v124, v124, v124 quad_perm:[1,0,3,2] row_mask:0xf bank_mask:0xf bound_ctrl:1
	s_nop 0
	s_nop 0
	v_add_f32_dpp v124, v124, v124 quad_perm:[2,3,0,1] row_mask:0xf bank_mask:0xf bound_ctrl:1
	s_nop 0
	s_nop 0
	v_add_f32_dpp v124, v124, v124 row_half_mirror row_mask:0xf bank_mask:0xf bound_ctrl:1
	s_nop 0
	s_nop 0
	v_add_f32_dpp v124, v124, v124 row_mirror row_mask:0xf bank_mask:0xf bound_ctrl:1
	v_pk_fma_f32 v[56:57], v[92:93], v[124:125], v[126:127] op_sel_hi:[1,0,1]
	v_pk_fma_f32 v[60:61], v[94:95], v[124:125], v[128:129] op_sel_hi:[1,0,1]
	v_pk_mul_f32 v[130:131], v[56:57], v[76:77]
	s_nop 0
	v_pk_fma_f32 v[130:131], v[60:61], v[78:79], v[130:131]
	s_nop 0
	v_add_f32_e32 v150, v130, v131
	s_waitcnt lgkmcnt(0)
	ds_read_b128 v[88:91], v72 offset:19200
	ds_read_b128 v[84:87], v72 offset:18944
	ds_read_b32 v96, v73 offset:19712
	ds_read_b128 v[80:83], v72 offset:18688
	ds_read_b128 v[92:95], v72 offset:19456
	ds_read_b128 v[76:79], v72 offset:18432
	v_pk_mul_f32 v[130:131], v[56:57], v[112:113]
	v_pk_mul_f32 v[126:127], v[108:109], v[120:121] op_sel_hi:[1,0]
	v_pk_fma_f32 v[130:131], v[60:61], v[114:115], v[130:131]
	v_pk_mul_f32 v[128:129], v[110:111], v[120:121] op_sel_hi:[1,0]
	v_add_f32_e32 v124, v130, v131
	v_pk_fma_f32 v[126:127], v[56:57], v[104:105], v[126:127]
	v_pk_fma_f32 v[128:129], v[60:61], v[106:107], v[128:129]
	v_add_f32_dpp v124, v124, v124 quad_perm:[1,0,3,2] row_mask:0xf bank_mask:0xf bound_ctrl:1
	s_nop 0
	s_nop 0
	v_add_f32_dpp v124, v124, v124 quad_perm:[2,3,0,1] row_mask:0xf bank_mask:0xf bound_ctrl:1
	s_nop 0
	s_nop 0
	v_add_f32_dpp v124, v124, v124 row_half_mirror row_mask:0xf bank_mask:0xf bound_ctrl:1
	s_nop 0
	s_nop 0
	v_add_f32_dpp v124, v124, v124 row_mirror row_mask:0xf bank_mask:0xf bound_ctrl:1
	v_pk_fma_f32 v[56:57], v[116:117], v[124:125], v[126:127] op_sel_hi:[1,0,1]
	v_pk_fma_f32 v[60:61], v[118:119], v[124:125], v[128:129] op_sel_hi:[1,0,1]
	v_pk_mul_f32 v[130:131], v[56:57], v[100:101]
	s_nop 0
	v_pk_fma_f32 v[130:131], v[60:61], v[102:103], v[130:131]
	s_nop 0
	v_add_f32_e32 v151, v130, v131
	s_waitcnt lgkmcnt(0)
; DI float dpp_xor1(float x) { return __int_as_float(__builtin_amdgcn_mov_dpp(__float_as_int(x), 0xB1, 0xF, 0xF, true)); }
; DI float dpp_xor2(float x) { return __int_as_float(__builtin_amdgcn_mov_dpp(__float_as_int(x), 0x4E, 0xF, 0xF, true)); }
; DI float dpp_hm(float x) { return __int_as_float(__builtin_amdgcn_mov_dpp(__float_as_int(x), 0x141, 0xF, 0xF, true)); }
; DI float dpp_rm(float x) { return __int_as_float(__builtin_amdgcn_mov_dpp(__float_as_int(x), 0x140, 0xF, 0xF, true)); }
; DI void rwkv_scan_task1(const Params& p, const Grp& G, int unit, char* lds) {
;     ...
;       for (int st = 0; st < 16; ++st) {
;         float4 kkB = kkA, wB = wA, kaB = kaA, kdB = kdA, rrB = rrA;
;         float vvB = vvA;
;         if (st < 15) {
;           const float* b = cur + (st + 1) * 384 + part * 4;
;           kkB = *(const float4*)(b + 3 * 64); wB = *(const float4*)(b + 1 * 64); kaB = *(const float4*)(b + 4 * 64);
;           kdB = *(const float4*)(b + 2 * 64); rrB = *(const float4*)(b);
;           vvB = cur[(st + 1) * 384 + 5 * 64 + vrow];
;         }
;         float ra = (S0 * kkA.x + S1 * kkA.y) + (S2 * kkA.z + S3 * kkA.w), rc = ypA;
;         ra += dpp_xor1(ra); rc += dpp_xor1(rc);
;         ra += dpp_xor2(ra); rc += dpp_xor2(rc);
;         ra += dpp_hm(ra); rc += dpp_hm(rc);
;         ra += dpp_rm(ra); rc += dpp_rm(rc);
;         if (st > 0) ykeep = (part == st - 1) ? rc : ykeep;
;         const float sa = ra;
;         S0 = S0 * wA.x + (sa * kaA.x + vvA * kdA.x);
;         S1 = S1 * wA.y + (sa * kaA.y + vvA * kdA.y);
;         S2 = S2 * wA.z + (sa * kaA.z + vvA * kdA.z);
;         S3 = S3 * wA.w + (sa * kaA.w + vvA * kdA.w);
;         ypA = (S0 * rrA.x + S1 * rrA.y) + (S2 * rrA.z + S3 * rrA.w);
;         kkA = kkB; wA = wB; kaA = kaB; kdA = kdB; rrA = rrB; vvA = vvB;
	ds_read_b128 v[112:115], v72 offset:20736
	ds_read_b128 v[108:111], v72 offset:20480
	ds_read_b32 v120, v73 offset:21248
	ds_read_b128 v[104:107], v72 offset:20224
	ds_read_b128 v[116:119], v72 offset:20992
	ds_read_b128 v[100:103], v72 offset:19968
	v_pk_mul_f32 v[130:131], v[56:57], v[88:89]
	v_pk_mul_f32 v[126:127], v[84:85], v[96:97] op_sel_hi:[1,0]
	v_pk_fma_f32 v[130:131], v[60:61], v[90:91], v[130:131]
	v_pk_mul_f32 v[128:129], v[86:87], v[96:97] op_sel_hi:[1,0]
	v_add_f32_e32 v124, v130, v131
	v_pk_fma_f32 v[126:127], v[56:57], v[80:81], v[126:127]
	v_pk_fma_f32 v[128:129], v[60:61], v[82:83], v[128:129]
	v_add_f32_dpp v124, v124, v124 quad_perm:[1,0,3,2] row_mask:0xf bank_mask:0xf bound_ctrl:1
	s_nop 0
	s_nop 0
	v_add_f32_dpp v124, v124, v124 quad_perm:[2,3,0,1] row_mask:0xf bank_mask:0xf bound_ctrl:1
	s_nop 0
	s_nop 0
	v_add_f32_dpp v124, v124, v124 row_half_mirror row_mask:0xf bank_mask:0xf bound_ctrl:1
	s_nop 0
	s_nop 0
	v_add_f32_dpp v124, v124, v124 row_mirror row_mask:0xf bank_mask:0xf bound_ctrl:1
	v_pk_fma_f32 v[56:57], v[92:93], v[124:125], v[126:127] op_sel_hi:[1,0,1]
	v_pk_fma_f32 v[60:61], v[94:95], v[124:125], v[128:129] op_sel_hi:[1,0,1]
	v_pk_mul_f32 v[130:131], v[56:57], v[76:77]
	s_nop 0
	v_pk_fma_f32 v[130:131], v[60:61], v[78:79], v[130:131]
	s_nop 0
	v_add_f32_e32 v152, v130, v131
	s_waitcnt lgkmcnt(0)
	ds_read_b128 v[88:91], v72 offset:22272
	ds_read_b128 v[84:87], v72 offset:22016
	ds_read_b32 v96, v73 offset:22784
	ds_read_b128 v[80:83], v72 offset:21760
	ds_read_b128 v[92:95], v72 offset:22528
	ds_read_b128 v[76:79], v72 offset:21504
	v_pk_mul_f32 v[130:131], v[56:57], v[112:113]
	v_pk_mul_f32 v[126:127], v[108:109], v[120:121] op_sel_hi:[1,0]
	v_pk_fma_f32 v[130:131], v[60:61], v[114:115], v[130:131]
	v_pk_mul_f32 v[128:129], v[110:111], v[120:121] op_sel_hi:[1,0]
	v_add_f32_e32 v124, v130, v131
	v_pk_fma_f32 v[126:127], v[56:57], v[104:105], v[126:127]
	v_pk_fma_f32 v[128:129], v[60:61], v[106:107], v[128:129]
	v_add_f32_dpp v124, v124, v124 quad_perm:[1,0,3,2] row_mask:0xf bank_mask:0xf bound_ctrl:1
	s_nop 0
	s_nop 0
	v_add_f32_dpp v124, v124, v124 quad_perm:[2,3,0,1] row_mask:0xf bank_mask:0xf bound_ctrl:1
	s_nop 0
	s_nop 0
	v_add_f32_dpp v124, v124, v124 row_half_mirror row_mask:0xf bank_mask:0xf bound_ctrl:1
	s_nop 0
	s_nop 0
	v_add_f32_dpp v124, v124, v124 row_mirror row_mask:0xf bank_mask:0xf bound_ctrl:1
	v_pk_fma_f32 v[56:57], v[116:117], v[124:125], v[126:127] op_sel_hi:[1,0,1]
	v_pk_fma_f32 v[60:61], v[118:119], v[124:125], v[128:129] op_sel_hi:[1,0,1]
	v_pk_mul_f32 v[130:131], v[56:57], v[100:101]
	s_nop 0
	v_pk_fma_f32 v[130:131], v[60:61], v[102:103], v[130:131]
	s_nop 0
	v_add_f32_e32 v153, v130, v131
	s_waitcnt lgkmcnt(0)
	ds_read_b128 v[112:115], v72 offset:23808
	ds_read_b128 v[108:111], v72 offset:23552
	ds_read_b32 v120, v73 offset:24320
	ds_read_b128 v[104:107], v72 offset:23296
	ds_read_b128 v[116:119], v72 offset:24064
	ds_read_b128 v[100:103], v72 offset:23040
	v_pk_mul_f32 v[130:131], v[56:57], v[88:89]
	v_pk_mul_f32 v[126:127], v[84:85], v[96:97] op_sel_hi:[1,0]
	v_pk_fma_f32 v[130:131], v[60:61], v[90:91], v[130:131]
	v_pk_mul_f32 v[128:129], v[86:87], v[96:97] op_sel_hi:[1,0]
	v_add_f32_e32 v124, v130, v131
	v_pk_fma_f32 v[126:127], v[56:57], v[80:81], v[126:127]
	v_pk_fma_f32 v[128:129], v[60:61], v[82:83], v[128:129]
	v_add_f32_dpp v124, v124, v124 quad_perm:[1,0,3,2] row_mask:0xf bank_mask:0xf bound_ctrl:1
	s_nop 0
	s_nop 0
	v_add_f32_dpp v124, v124, v124 quad_perm:[2,3,0,1] row_mask:0xf bank_mask:0xf bound_ctrl:1
	s_nop 0
	s_nop 0
	v_add_f32_dpp v124, v124, v124 row_half_mirror row_mask:0xf bank_mask:0xf bound_ctrl:1
	s_nop 0
	s_nop 0
	v_add_f32_dpp v124, v124, v124 row_mirror row_mask:0xf bank_mask:0xf bound_ctrl:1
	v_pk_fma_f32 v[56:57], v[92:93], v[124:125], v[126:127] op_sel_hi:[1,0,1]
	v_pk_fma_f32 v[60:61], v[94:95], v[124:125], v[128:129] op_sel_hi:[1,0,1]
	v_pk_mul_f32 v[130:131], v[56:57], v[76:77]
	s_nop 0
	v_pk_fma_f32 v[130:131], v[60:61], v[78:79], v[130:131]
	s_nop 0
	v_add_f32_e32 v154, v130, v131
	s_waitcnt lgkmcnt(0)
; DI bf16_t f2bf(float f) { return (bf16_t)(pack2(f, f) & 0xffffu); }
; DI float lo2f(unsigned u) { return __uint_as_float(u << 16); }
; DI float hi2f(unsigned u) { return __uint_as_float(u & 0xffff0000u); }
; DI float dpp_xor1(float x) { return __int_as_float(__builtin_amdgcn_mov_dpp(__float_as_int(x), 0xB1, 0xF, 0xF, true)); }
; DI float dpp_xor2(float x) { return __int_as_float(__builtin_amdgcn_mov_dpp(__float_as_int(x), 0x4E, 0xF, 0xF, true)); }
; DI float dpp_hm(float x) { return __int_as_float(__builtin_amdgcn_mov_dpp(__float_as_int(x), 0x141, 0xF, 0xF, true)); }
; DI float dpp_rm(float x) { return __int_as_float(__builtin_amdgcn_mov_dpp(__float_as_int(x), 0x140, 0xF, 0xF, true)); }
; DI float row16_sum(float x) { x += dpp_xor1(x); x += dpp_xor2(x); x += dpp_hm(x); x += dpp_rm(x); return x; }
; DI void rwkv_scan_task1(const Params& p, const Grp& G, int unit, char* lds) {
;     ...
;         float ra = (S0 * kkA.x + S1 * kkA.y) + (S2 * kkA.z + S3 * kkA.w), rc = ypA;
;         ra += dpp_xor1(ra); rc += dpp_xor1(rc);
;         ra += dpp_xor2(ra); rc += dpp_xor2(rc);
;         ra += dpp_hm(ra); rc += dpp_hm(rc);
;         ra += dpp_rm(ra); rc += dpp_rm(rc);
;         if (st > 0) ykeep = (part == st - 1) ? rc : ykeep;
;         const float sa = ra;
;         S0 = S0 * wA.x + (sa * kaA.x + vvA * kdA.x);
;         S1 = S1 * wA.y + (sa * kaA.y + vvA * kdA.y);
;         S2 = S2 * wA.z + (sa * kaA.z + vvA * kdA.z);
;         S3 = S3 * wA.w + (sa * kaA.w + vvA * kdA.w);
;         ypA = (S0 * rrA.x + S1 * rrA.y) + (S2 * rrA.z + S3 * rrA.w);
;         kkA = kkB; wA = wB; kaA = kaB; kdA = kdB; rrA = rrB; vvA = vvB;
;       }
;       {
;         float y15 = row16_sum(ypA);
;         ykeep = (part == 15) ? y15 : ykeep;
;         int s = tl * 16 + part, pos = dir ? G.len - 1 - s : s;
;         obase[(size_t)pos * RAWC] = f2bf(ykeep);
;       }
;     }
;     if (tl + 1 < ntile) {
; #pragma unroll
;       for (int i = 0; i < 3; ++i) {
;         float* d = nxt + ldst[i];
;         *(float4*)d = make_float4(lo2f(rg[i].x), hi2f(rg[i].x), lo2f(rg[i].y), hi2f(rg[i].y));
;         *(float4*)(d + 4) = make_float4(lo2f(rg[i].z), hi2f(rg[i].z), lo2f(rg[i].w), hi2f(rg[i].w));
;       }
;     }
;     __syncthreads();
	v_pk_mul_f32 v[130:131], v[56:57], v[112:113]
	v_pk_mul_f32 v[126:127], v[108:109], v[120:121] op_sel_hi:[1,0]
	v_pk_fma_f32 v[130:131], v[60:61], v[114:115], v[130:131]
	v_pk_mul_f32 v[128:129], v[110:111], v[120:121] op_sel_hi:[1,0]
	v_add_f32_e32 v124, v130, v131
	v_pk_fma_f32 v[126:127], v[56:57], v[104:105], v[126:127]
	v_pk_fma_f32 v[128:129], v[60:61], v[106:107], v[128:129]
	v_add_f32_dpp v124, v124, v124 quad_perm:[1,0,3,2] row_mask:0xf bank_mask:0xf bound_ctrl:1
	s_nop 0
	s_nop 0
	v_add_f32_dpp v124, v124, v124 quad_perm:[2,3,0,1] row_mask:0xf bank_mask:0xf bound_ctrl:1
	s_nop 0
	s_nop 0
	v_add_f32_dpp v124, v124, v124 row_half_mirror row_mask:0xf bank_mask:0xf bound_ctrl:1
	s_nop 0
	s_nop 0
	v_add_f32_dpp v124, v124, v124 row_mirror row_mask:0xf bank_mask:0xf bound_ctrl:1
	v_pk_fma_f32 v[56:57], v[116:117], v[124:125], v[126:127] op_sel_hi:[1,0,1]
	v_pk_fma_f32 v[60:61], v[118:119], v[124:125], v[128:129] op_sel_hi:[1,0,1]
	v_pk_mul_f32 v[130:131], v[56:57], v[100:101]
	s_nop 0
	v_pk_fma_f32 v[130:131], v[60:61], v[102:103], v[130:131]
	s_nop 0
	v_add_f32_e32 v155, v130, v131
	v_add_f32_dpp v140, v140, v140 row_ror:8 row_mask:0xf bank_mask:0x3 bound_ctrl:1
	v_add_f32_dpp v140, v141, v141 row_ror:8 row_mask:0xf bank_mask:0xc bound_ctrl:1
	v_add_f32_dpp v142, v142, v142 row_ror:8 row_mask:0xf bank_mask:0x3 bound_ctrl:1
	v_add_f32_dpp v142, v143, v143 row_ror:8 row_mask:0xf bank_mask:0xc bound_ctrl:1
	v_add_f32_dpp v144, v144, v144 row_ror:8 row_mask:0xf bank_mask:0x3 bound_ctrl:1
	v_add_f32_dpp v144, v145, v145 row_ror:8 row_mask:0xf bank_mask:0xc bound_ctrl:1
	v_add_f32_dpp v146, v146, v146 row_ror:8 row_mask:0xf bank_mask:0x3 bound_ctrl:1
	v_add_f32_dpp v146, v147, v147 row_ror:8 row_mask:0xf bank_mask:0xc bound_ctrl:1
	v_add_f32_dpp v148, v148, v148 row_ror:8 row_mask:0xf bank_mask:0x3 bound_ctrl:1
	v_add_f32_dpp v148, v149, v149 row_ror:8 row_mask:0xf bank_mask:0xc bound_ctrl:1
	v_add_f32_dpp v150, v150, v150 row_ror:8 row_mask:0xf bank_mask:0x3 bound_ctrl:1
	v_add_f32_dpp v150, v151, v151 row_ror:8 row_mask:0xf bank_mask:0xc bound_ctrl:1
	v_add_f32_dpp v152, v152, v152 row_ror:8 row_mask:0xf bank_mask:0x3 bound_ctrl:1
	v_add_f32_dpp v152, v153, v153 row_ror:8 row_mask:0xf bank_mask:0xc bound_ctrl:1
	v_add_f32_dpp v154, v154, v154 row_ror:8 row_mask:0xf bank_mask:0x3 bound_ctrl:1
	v_add_f32_dpp v154, v155, v155 row_ror:8 row_mask:0xf bank_mask:0xc bound_ctrl:1
	v_add_f32_dpp v140, v140, v140 row_shl:4 row_mask:0xf bank_mask:0x5 bound_ctrl:1
	v_add_f32_dpp v140, v142, v142 row_shr:4 row_mask:0xf bank_mask:0xa bound_ctrl:1
	v_add_f32_dpp v144, v144, v144 row_shl:4 row_mask:0xf bank_mask:0x5 bound_ctrl:1
	v_add_f32_dpp v144, v146, v146 row_shr:4 row_mask:0xf bank_mask:0xa bound_ctrl:1
	v_add_f32_dpp v148, v148, v148 row_shl:4 row_mask:0xf bank_mask:0x5 bound_ctrl:1
	v_add_f32_dpp v148, v150, v150 row_shr:4 row_mask:0xf bank_mask:0xa bound_ctrl:1
	v_add_f32_dpp v152, v152, v152 row_shl:4 row_mask:0xf bank_mask:0x5 bound_ctrl:1
	v_add_f32_dpp v152, v154, v154 row_shr:4 row_mask:0xf bank_mask:0xa bound_ctrl:1
	v_add_f32_dpp v140, v140, v140 quad_perm:[1,0,3,2] row_mask:0xf bank_mask:0xf bound_ctrl:1
	v_add_f32_dpp v144, v144, v144 quad_perm:[1,0,3,2] row_mask:0xf bank_mask:0xf bound_ctrl:1
	v_add_f32_dpp v148, v148, v148 quad_perm:[1,0,3,2] row_mask:0xf bank_mask:0xf bound_ctrl:1
	v_add_f32_dpp v152, v152, v152 quad_perm:[1,0,3,2] row_mask:0xf bank_mask:0xf bound_ctrl:1
	v_add_f32_dpp v140, v140, v140 quad_perm:[2,3,0,1] row_mask:0xf bank_mask:0xf bound_ctrl:1
	v_add_f32_dpp v144, v144, v144 quad_perm:[2,3,0,1] row_mask:0xf bank_mask:0xf bound_ctrl:1
	v_add_f32_dpp v148, v148, v148 quad_perm:[2,3,0,1] row_mask:0xf bank_mask:0xf bound_ctrl:1
	v_add_f32_dpp v152, v152, v152 quad_perm:[2,3,0,1] row_mask:0xf bank_mask:0xf bound_ctrl:1
	v_and_b32_e32 v136, 3, v65
	v_bfe_u32 v137, v65, 2, 1
	v_lshrrev_b32_e32 v138, 3, v65
	v_lshl_add_u32 v139, v137, 1, v138
	v_lshl_add_u32 v139, v136, 2, v139
	v_sub_u32_e32 v137, v65, v139
	v_add_u32_e32 v137, v0, v137
	v_add_u32_e32 v134, s40, v139
	v_cndmask_b32_e64 v134, v137, v134, s[4:5]
	v_ashrrev_i32_e32 v135, 31, v134
	v_lshlrev_b64 v[134:135], 13, v[134:135]
	v_lshl_add_u64 v[134:135], v[48:49], 0, v[134:135]
	v_cmp_lt_u32_e32 vcc, 0, v136
	s_nop 1
	v_cndmask_b32_e32 v140, v140, v144, vcc
	v_cmp_lt_u32_e32 vcc, 1, v136
	s_nop 1
	v_cndmask_b32_e32 v140, v140, v148, vcc
	v_cmp_lt_u32_e32 vcc, 2, v136
	s_nop 1
	v_cndmask_b32_e32 v140, v140, v152, vcc
	v_cvt_pk_bf16_f32 v132, v140, v140
	s_andn2_b64 vcc, exec, s[0:1]
	global_store_short v[134:135], v132, off
	s_cbranch_vccnz .LBB0_874
	s_bitcmp1_b32 s41, 0
	s_cselect_b32 s0, 0x6000, 0
	v_lshl_add_u32 v18, v63, 2, s0
	s_waitcnt vmcnt(3)
	v_lshlrev_b32_e32 v14, 16, v2
	v_and_b32_e32 v15, 0xffff0000, v2
	v_lshlrev_b32_e32 v16, 16, v3
	v_and_b32_e32 v17, 0xffff0000, v3
	ds_write_b128 v18, v[14:17]
	v_lshlrev_b32_e32 v14, 16, v4
	v_and_b32_e32 v15, 0xffff0000, v4
	v_lshlrev_b32_e32 v16, 16, v5
	v_and_b32_e32 v17, 0xffff0000, v5
	ds_write_b128 v18, v[14:17] offset:16
	v_lshl_add_u32 v18, v62, 2, s0
	s_waitcnt vmcnt(2)
	v_lshlrev_b32_e32 v14, 16, v6
	v_and_b32_e32 v15, 0xffff0000, v6
	v_lshlrev_b32_e32 v16, 16, v7
	v_and_b32_e32 v17, 0xffff0000, v7
	ds_write_b128 v18, v[14:17]
	v_lshlrev_b32_e32 v14, 16, v8
	v_and_b32_e32 v15, 0xffff0000, v8
	v_lshlrev_b32_e32 v16, 16, v9
	v_and_b32_e32 v17, 0xffff0000, v9
	ds_write_b128 v18, v[14:17] offset:16
	v_lshl_add_u32 v18, v64, 2, s0
	s_waitcnt vmcnt(1)
	v_lshlrev_b32_e32 v14, 16, v10
	v_and_b32_e32 v15, 0xffff0000, v10
	v_lshlrev_b32_e32 v16, 16, v11
	v_and_b32_e32 v17, 0xffff0000, v11
	ds_write_b128 v18, v[14:17]
	v_lshlrev_b32_e32 v14, 16, v12
	v_and_b32_e32 v15, 0xffff0000, v12
	v_lshlrev_b32_e32 v16, 16, v13
	v_and_b32_e32 v17, 0xffff0000, v13
	ds_write_b128 v18, v[14:17] offset:16
	s_branch .LBB0_874
